# down/out/o GEMM loops: first K iteration peeled with SrcC=0, the 128 v_mov_b64 accumulator zeroing moves per phase removed
# speedup vs baseline: 1.0110x; 1.0110x over previous
.LBB7_423:
	s_and_b32 s96, s12, 3
	s_lshl_b32 s14, s10, 13
	s_lshl_b32 s15, s96, 12
	s_add_u32 s12, s8, 0x8000
	v_mov_b32_e32 v177, v1
	s_addc_u32 s13, s9, 0
	v_mov_b32_e32 v161, v1
	s_add_i32 m0, s23, 0x18000
	v_lshl_add_u64 v[8:9], s[12:13], 0, v[176:177]
	s_waitcnt vmcnt(2)
	s_barrier
	global_load_lds_dwordx4 v[8:9], off
	v_lshl_add_u64 v[8:9], s[12:13], 0, v[160:161]
	v_readlane_b32 s12, v253, 11
	v_mov_b32_e32 v179, v1
	s_add_i32 m0, s23, 0x1a000
	v_readlane_b32 s13, v253, 12
	s_add_i32 s97, s23, 0x8000
	v_mov_b32_e32 v175, v1
	global_load_lds_dwordx4 v[8:9], off
	v_lshl_add_u64 v[8:9], s[12:13], 0, v[178:179]
	s_mov_b32 m0, s97
	s_add_i32 s38, s23, 0xa000
	global_load_lds_dwordx4 v[8:9], off
	v_lshl_add_u64 v[8:9], s[12:13], 0, v[174:175]
	s_add_u32 s12, s8, 0xc000
	s_mov_b32 m0, s38
	s_addc_u32 s13, s9, 0
	global_load_lds_dwordx4 v[8:9], off
	s_add_i32 m0, s23, 0x1c000
	v_lshl_add_u64 v[8:9], s[12:13], 0, v[176:177]
	global_load_lds_dwordx4 v[8:9], off
	v_lshl_add_u64 v[8:9], s[12:13], 0, v[160:161]
	s_add_i32 m0, s23, 0x1e000
	s_cmpk_lt_u32 s3, 0x100
	global_load_lds_dwordx4 v[8:9], off
	v_bfe_u32 v9, v0, 4, 2
	v_and_b32_e32 v8, 15, v0
	v_lshlrev_b32_e32 v11, 4, v9
	v_lshlrev_b32_e32 v0, 2, v0
	v_lshl_or_b32 v204, s10, 6, v8
	v_lshl_or_b32 v8, v8, 6, v11
	v_and_b32_e32 v0, 32, v0
	v_bitop3_b32 v11, v8, s14, v0 bitop3:0xde
	v_bitop3_b32 v205, v8, s15, v0 bitop3:0xde
	v_lshlrev_b32_e32 v0, 10, v6
	v_and_b32_e32 v0, 0xfffff800, v0
	v_lshl_add_u32 v0, v5, 7, v0
	v_and_b32_e32 v5, 1, v6
	v_lshl_or_b32 v0, v5, 6, v0
	v_lshl_add_u32 v180, v7, 1, v0
	v_lshlrev_b32_e32 v0, 10, v2
	v_and_b32_e32 v0, 0xfffff800, v0
	v_lshl_add_u32 v0, v3, 7, v0
	v_and_b32_e32 v2, 1, v2
	v_lshlrev_b32_e32 v10, 3, v9
	s_waitcnt vmcnt(6)
	v_lshl_or_b32 v0, v2, 6, v0
	v_mov_b32_e32 v2, v1
	v_mov_b32_e32 v3, v1
	v_lshl_or_b32 v206, s96, 5, v10
	s_cselect_b64 s[12:13], -1, 0
	v_cmp_eq_u32_e64 s[40:41], 0, v9
	s_cmp_gt_i32 s39, 0
	v_lshl_add_u32 v182, v4, 1, v0
	v_mov_b32_e32 v0, v1
	v_add_u32_e32 v207, 0, v11
	s_waitcnt vmcnt(0)
	v_readlane_b32 s16, v253, 5
	v_readlane_b32 s18, v253, 9
	s_mov_b32 s28, 0
	s_cselect_b64 s[14:15], -1, 0
	s_add_i32 s3, s39, -2
	v_mov_b32_e32 v181, v1
	v_mov_b32_e32 v183, v1
	v_readlane_b32 s10, v252, 22
	s_mov_b32 s89, s16
	v_readlane_b32 s19, v253, 10
	s_barrier
	v_readlane_b32 s17, v253, 6
	s_branch .LBB7_426
.LBB7_424:
	s_waitcnt lgkmcnt(0)
	v_mov_b32_e32 v2, v1
	v_mov_b32_e32 v3, v1
	v_mov_b32_e32 v0, v1
	s_mov_b32 s10, s57
	s_mov_b32 s89, s88
	s_mov_b64 s[8:9], s[54:55]
	s_mov_b64 s[18:19], s[52:53]
	s_mov_b32 s28, s56

.Lpeel_434:
	s_add_i32 s75, s72, 2
	s_add_u32 s76, s16, 0x4000
	s_addc_u32 s73, s17, 0
	s_cmp_eq_u32 s3, s72
	s_cselect_b32 s72, s86, s76
	s_cselect_b32 s73, s20, s73
	s_cselect_b32 s84, s37, s29
	s_cselect_b32 s85, s87, s74
	s_add_u32 vcc_lo, s72, 0x8000
	s_addc_u32 vcc_hi, s73, 0
	s_add_i32 s76, 0, 0x10000
	v_add_u32_e32 v0, s76, v205
	s_add_i32 s91, 0, 0x14000
	ds_read_b128 v[132:135], v0
	ds_read_b128 v[136:139], v0 offset:1024
	ds_read_b128 v[140:143], v0 offset:2048
	ds_read_b128 v[144:147], v0 offset:3072
	v_add_u32_e32 v0, s91, v205
	ds_read_b128 v[148:151], v0
	ds_read_b128 v[152:155], v0 offset:1024
	ds_read_b128 v[156:159], v0 offset:2048
	ds_read_b128 v[184:187], v0 offset:3072
	s_waitcnt lgkmcnt(0)
	s_add_i32 m0, s23, 0xc000
	ds_read_b128 v[188:191], v207
	ds_read_b128 v[192:195], v207 offset:1024
	ds_read_b128 v[196:199], v207 offset:2048
	ds_read_b128 v[208:211], v207 offset:3072
	ds_read_b128 v[212:215], v207 offset:4096
	ds_read_b128 v[216:219], v207 offset:5120
	ds_read_b128 v[220:223], v207 offset:6144
	ds_read_b128 v[224:227], v207 offset:7168
	global_load_lds_dwordx4 v180, s[16:17]
	s_add_i32 m0, s23, 0xe000
	s_nop 0
	global_load_lds_dwordx4 v182, s[16:17]
	s_waitcnt vmcnt(8)
	s_waitcnt lgkmcnt(0)
	s_setprio 1
	s_barrier
	v_mfma_f32_16x16x32_bf16 v[128:131], v[132:135], v[188:191], 0
	v_mfma_f32_16x16x32_bf16 v[124:127], v[140:143], v[188:191], 0
	v_mfma_f32_16x16x32_bf16 v[120:123], v[132:135], v[196:199], 0
	v_mfma_f32_16x16x32_bf16 v[116:119], v[140:143], v[196:199], 0
	v_mfma_f32_16x16x32_bf16 v[112:115], v[132:135], v[212:215], 0
	v_mfma_f32_16x16x32_bf16 v[108:111], v[140:143], v[212:215], 0
	v_mfma_f32_16x16x32_bf16 v[104:107], v[132:135], v[220:223], 0
	v_mfma_f32_16x16x32_bf16 v[100:103], v[140:143], v[220:223], 0
	v_mfma_f32_16x16x32_bf16 v[128:131], v[136:139], v[192:195], v[128:131]
	v_mfma_f32_16x16x32_bf16 v[124:127], v[144:147], v[192:195], v[124:127]
	v_mfma_f32_16x16x32_bf16 v[120:123], v[136:139], v[208:211], v[120:123]
	v_mfma_f32_16x16x32_bf16 v[116:119], v[144:147], v[208:211], v[116:119]
	v_mfma_f32_16x16x32_bf16 v[112:115], v[136:139], v[216:219], v[112:115]
	v_mfma_f32_16x16x32_bf16 v[108:111], v[144:147], v[216:219], v[108:111]
	v_mfma_f32_16x16x32_bf16 v[104:107], v[136:139], v[224:227], v[104:107]
	v_mfma_f32_16x16x32_bf16 v[100:103], v[144:147], v[224:227], v[100:103]
	v_mfma_f32_16x16x32_bf16 v[96:99], v[148:151], v[188:191], 0
	v_mfma_f32_16x16x32_bf16 v[92:95], v[156:159], v[188:191], 0
	v_mfma_f32_16x16x32_bf16 v[88:91], v[148:151], v[196:199], 0
	v_mfma_f32_16x16x32_bf16 v[84:87], v[156:159], v[196:199], 0
	v_mfma_f32_16x16x32_bf16 v[80:83], v[148:151], v[212:215], 0
	v_mfma_f32_16x16x32_bf16 v[76:79], v[156:159], v[212:215], 0
	v_mfma_f32_16x16x32_bf16 v[72:75], v[148:151], v[220:223], 0
	v_mfma_f32_16x16x32_bf16 v[64:67], v[156:159], v[220:223], 0
	v_mfma_f32_16x16x32_bf16 v[96:99], v[152:155], v[192:195], v[96:99]
	v_mfma_f32_16x16x32_bf16 v[92:95], v[184:187], v[192:195], v[92:95]
	v_mfma_f32_16x16x32_bf16 v[88:91], v[152:155], v[208:211], v[88:91]
	v_mfma_f32_16x16x32_bf16 v[84:87], v[184:187], v[208:211], v[84:87]
	v_mfma_f32_16x16x32_bf16 v[80:83], v[152:155], v[216:219], v[80:83]
	v_mfma_f32_16x16x32_bf16 v[76:79], v[184:187], v[216:219], v[76:79]
	v_mfma_f32_16x16x32_bf16 v[72:75], v[152:155], v[224:227], v[72:75]
	v_mfma_f32_16x16x32_bf16 v[64:67], v[184:187], v[224:227], v[64:67]
	s_barrier
	s_setprio 0
	s_add_i32 s76, s76, s4
	s_mov_b32 m0, s76
	ds_read_b128 v[188:191], v207 offset:16384
	ds_read_b128 v[192:195], v207 offset:17408
	ds_read_b128 v[196:199], v207 offset:18432
	ds_read_b128 v[208:211], v207 offset:19456
	ds_read_b128 v[212:215], v207 offset:20480
	ds_read_b128 v[216:219], v207 offset:21504
	ds_read_b128 v[220:223], v207 offset:22528
	ds_read_b128 v[224:227], v207 offset:23552
	global_load_lds_dwordx4 v176, s[84:85]
	s_add_i32 m0, s76, 0x2000
	s_add_u32 s76, s84, 0x4000
	s_addc_u32 s77, s85, 0
	s_add_i32 s91, s91, s4
	global_load_lds_dwordx4 v160, s[84:85]
	s_mov_b32 m0, s91
	s_nop 0
	global_load_lds_dwordx4 v176, s[76:77]
	s_add_i32 m0, s91, 0x2000
	s_nop 0
	global_load_lds_dwordx4 v160, s[76:77]
	s_mov_b32 m0, s23
	s_nop 0
	global_load_lds_dwordx4 v178, s[72:73]
	s_mov_b32 m0, s31
	s_nop 0
	global_load_lds_dwordx4 v174, s[72:73]
	s_waitcnt vmcnt(8)
	s_waitcnt lgkmcnt(0)
	s_setprio 1
	s_barrier
	v_mfma_f32_16x16x32_bf16 v[68:71], v[132:135], v[188:191], 0
	v_mfma_f32_16x16x32_bf16 v[60:63], v[140:143], v[188:191], 0
	v_mfma_f32_16x16x32_bf16 v[56:59], v[132:135], v[196:199], 0
	v_mfma_f32_16x16x32_bf16 v[52:55], v[140:143], v[196:199], 0
	v_mfma_f32_16x16x32_bf16 v[48:51], v[132:135], v[212:215], 0
	v_mfma_f32_16x16x32_bf16 v[44:47], v[140:143], v[212:215], 0
	v_mfma_f32_16x16x32_bf16 v[40:43], v[132:135], v[220:223], 0
	v_mfma_f32_16x16x32_bf16 v[36:39], v[140:143], v[220:223], 0
	v_mfma_f32_16x16x32_bf16 v[68:71], v[136:139], v[192:195], v[68:71]
	v_mfma_f32_16x16x32_bf16 v[60:63], v[144:147], v[192:195], v[60:63]
	v_mfma_f32_16x16x32_bf16 v[56:59], v[136:139], v[208:211], v[56:59]
	v_mfma_f32_16x16x32_bf16 v[52:55], v[144:147], v[208:211], v[52:55]
	v_mfma_f32_16x16x32_bf16 v[48:51], v[136:139], v[216:219], v[48:51]
	v_mfma_f32_16x16x32_bf16 v[44:47], v[144:147], v[216:219], v[44:47]
	v_mfma_f32_16x16x32_bf16 v[40:43], v[136:139], v[224:227], v[40:43]
	v_mfma_f32_16x16x32_bf16 v[36:39], v[144:147], v[224:227], v[36:39]
	v_mfma_f32_16x16x32_bf16 v[32:35], v[148:151], v[188:191], 0
	v_mfma_f32_16x16x32_bf16 v[28:31], v[156:159], v[188:191], 0
	v_mfma_f32_16x16x32_bf16 v[24:27], v[148:151], v[196:199], 0
	v_mfma_f32_16x16x32_bf16 v[20:23], v[156:159], v[196:199], 0
	v_mfma_f32_16x16x32_bf16 v[16:19], v[148:151], v[212:215], 0
	v_mfma_f32_16x16x32_bf16 v[12:15], v[156:159], v[212:215], 0
	v_mfma_f32_16x16x32_bf16 v[8:11], v[148:151], v[220:223], 0
	v_mfma_f32_16x16x32_bf16 v[2:5], v[156:159], v[220:223], 0
	v_mfma_f32_16x16x32_bf16 v[32:35], v[152:155], v[192:195], v[32:35]
	v_mfma_f32_16x16x32_bf16 v[28:31], v[184:187], v[192:195], v[28:31]
	v_mfma_f32_16x16x32_bf16 v[24:27], v[152:155], v[208:211], v[24:27]
	v_mfma_f32_16x16x32_bf16 v[20:23], v[184:187], v[208:211], v[20:23]
	v_mfma_f32_16x16x32_bf16 v[16:19], v[152:155], v[216:219], v[16:19]
	v_mfma_f32_16x16x32_bf16 v[12:15], v[184:187], v[216:219], v[12:15]
	v_mfma_f32_16x16x32_bf16 v[8:11], v[152:155], v[224:227], v[8:11]
	v_mfma_f32_16x16x32_bf16 v[2:5], v[184:187], v[224:227], v[2:5]
	s_barrier
	s_setprio 0
	s_add_i32 s76, 0, 0x18000
	v_add_u32_e32 v0, s76, v205
	s_add_i32 s77, 0, 0x1c000
	ds_read_b128 v[132:135], v0
	ds_read_b128 v[136:139], v0 offset:1024
	ds_read_b128 v[140:143], v0 offset:2048
	ds_read_b128 v[144:147], v0 offset:3072
	v_add_u32_e32 v0, s77, v205
	ds_read_b128 v[148:151], v0
	ds_read_b128 v[152:155], v0 offset:1024
	ds_read_b128 v[156:159], v0 offset:2048
	ds_read_b128 v[184:187], v0 offset:3072
	s_add_u32 s72, s72, 0x4000
	s_addc_u32 s73, s73, 0
	s_mov_b32 m0, s33
	ds_read_b128 v[188:191], v207 offset:32768
	ds_read_b128 v[192:195], v207 offset:33792
	ds_read_b128 v[196:199], v207 offset:34816
	ds_read_b128 v[208:211], v207 offset:35840
	ds_read_b128 v[212:215], v207 offset:36864
	ds_read_b128 v[216:219], v207 offset:37888
	ds_read_b128 v[220:223], v207 offset:38912
	ds_read_b128 v[224:227], v207 offset:39936
	global_load_lds_dwordx4 v178, s[72:73]
	s_mov_b32 m0, s93
	s_nop 0
	global_load_lds_dwordx4 v174, s[72:73]
	s_waitcnt vmcnt(8)
	s_waitcnt lgkmcnt(0)
	s_setprio 1
	s_barrier
	v_mfma_f32_16x16x32_bf16 v[128:131], v[132:135], v[188:191], v[128:131]
	v_mfma_f32_16x16x32_bf16 v[124:127], v[140:143], v[188:191], v[124:127]
	v_mfma_f32_16x16x32_bf16 v[120:123], v[132:135], v[196:199], v[120:123]
	v_mfma_f32_16x16x32_bf16 v[116:119], v[140:143], v[196:199], v[116:119]
	v_mfma_f32_16x16x32_bf16 v[112:115], v[132:135], v[212:215], v[112:115]
	v_mfma_f32_16x16x32_bf16 v[108:111], v[140:143], v[212:215], v[108:111]
	v_mfma_f32_16x16x32_bf16 v[104:107], v[132:135], v[220:223], v[104:107]
	v_mfma_f32_16x16x32_bf16 v[100:103], v[140:143], v[220:223], v[100:103]
	v_mfma_f32_16x16x32_bf16 v[128:131], v[136:139], v[192:195], v[128:131]
	v_mfma_f32_16x16x32_bf16 v[124:127], v[144:147], v[192:195], v[124:127]
	v_mfma_f32_16x16x32_bf16 v[120:123], v[136:139], v[208:211], v[120:123]
	v_mfma_f32_16x16x32_bf16 v[116:119], v[144:147], v[208:211], v[116:119]
	v_mfma_f32_16x16x32_bf16 v[112:115], v[136:139], v[216:219], v[112:115]
	v_mfma_f32_16x16x32_bf16 v[108:111], v[144:147], v[216:219], v[108:111]
	v_mfma_f32_16x16x32_bf16 v[104:107], v[136:139], v[224:227], v[104:107]
	v_mfma_f32_16x16x32_bf16 v[100:103], v[144:147], v[224:227], v[100:103]
	v_mfma_f32_16x16x32_bf16 v[96:99], v[148:151], v[188:191], v[96:99]
	v_mfma_f32_16x16x32_bf16 v[92:95], v[156:159], v[188:191], v[92:95]
	v_mfma_f32_16x16x32_bf16 v[88:91], v[148:151], v[196:199], v[88:91]
	v_mfma_f32_16x16x32_bf16 v[84:87], v[156:159], v[196:199], v[84:87]
	v_mfma_f32_16x16x32_bf16 v[80:83], v[148:151], v[212:215], v[80:83]
	v_mfma_f32_16x16x32_bf16 v[76:79], v[156:159], v[212:215], v[76:79]
	v_mfma_f32_16x16x32_bf16 v[72:75], v[148:151], v[220:223], v[72:75]
	v_mfma_f32_16x16x32_bf16 v[64:67], v[156:159], v[220:223], v[64:67]
	v_mfma_f32_16x16x32_bf16 v[96:99], v[152:155], v[192:195], v[96:99]
	v_mfma_f32_16x16x32_bf16 v[92:95], v[184:187], v[192:195], v[92:95]
	v_mfma_f32_16x16x32_bf16 v[88:91], v[152:155], v[208:211], v[88:91]
	v_mfma_f32_16x16x32_bf16 v[84:87], v[184:187], v[208:211], v[84:87]
	v_mfma_f32_16x16x32_bf16 v[80:83], v[152:155], v[216:219], v[80:83]
	v_mfma_f32_16x16x32_bf16 v[76:79], v[184:187], v[216:219], v[76:79]
	v_mfma_f32_16x16x32_bf16 v[72:75], v[152:155], v[224:227], v[72:75]
	v_mfma_f32_16x16x32_bf16 v[64:67], v[184:187], v[224:227], v[64:67]
	s_barrier
	s_setprio 0
	s_add_u32 s72, s84, 0x8000
	s_addc_u32 s73, s85, 0
	s_add_i32 s76, s76, s4
	s_mov_b32 m0, s76
	ds_read_b128 v[188:191], v207 offset:49152
	ds_read_b128 v[192:195], v207 offset:50176
	ds_read_b128 v[196:199], v207 offset:51200
	ds_read_b128 v[208:211], v207 offset:52224
	ds_read_b128 v[212:215], v207 offset:53248
	ds_read_b128 v[216:219], v207 offset:54272
	ds_read_b128 v[220:223], v207 offset:55296
	ds_read_b128 v[224:227], v207 offset:56320
	global_load_lds_dwordx4 v176, s[72:73]
	s_add_i32 m0, s76, 0x2000
	v_lshl_add_u64 v[6:7], s[72:73], 0, v[160:161]
	s_add_u32 s72, s84, 0xc000
	s_addc_u32 s73, s85, 0
	s_add_i32 s76, s77, s4
	global_load_lds_dwordx4 v[6:7], off
	s_mov_b32 m0, s76
	s_nop 0
	global_load_lds_dwordx4 v176, s[72:73]
	s_add_i32 m0, s76, 0x2000
	s_nop 0
	global_load_lds_dwordx4 v160, s[72:73]
	s_mov_b32 m0, s97
	s_nop 0
	global_load_lds_dwordx4 v178, vcc
	s_mov_b32 m0, s38
	s_nop 0
	global_load_lds_dwordx4 v174, vcc
	s_waitcnt vmcnt(8)
	s_waitcnt lgkmcnt(0)
	s_setprio 1
	s_barrier
	v_mfma_f32_16x16x32_bf16 v[68:71], v[132:135], v[188:191], v[68:71]
	v_mfma_f32_16x16x32_bf16 v[60:63], v[140:143], v[188:191], v[60:63]
	v_mfma_f32_16x16x32_bf16 v[56:59], v[132:135], v[196:199], v[56:59]
	v_mfma_f32_16x16x32_bf16 v[52:55], v[140:143], v[196:199], v[52:55]
	v_mfma_f32_16x16x32_bf16 v[48:51], v[132:135], v[212:215], v[48:51]
	v_mfma_f32_16x16x32_bf16 v[44:47], v[140:143], v[212:215], v[44:47]
	v_mfma_f32_16x16x32_bf16 v[40:43], v[132:135], v[220:223], v[40:43]
	v_mfma_f32_16x16x32_bf16 v[36:39], v[140:143], v[220:223], v[36:39]
	v_mfma_f32_16x16x32_bf16 v[68:71], v[136:139], v[192:195], v[68:71]
	v_mfma_f32_16x16x32_bf16 v[60:63], v[144:147], v[192:195], v[60:63]
	v_mfma_f32_16x16x32_bf16 v[56:59], v[136:139], v[208:211], v[56:59]
	v_mfma_f32_16x16x32_bf16 v[52:55], v[144:147], v[208:211], v[52:55]
	v_mfma_f32_16x16x32_bf16 v[48:51], v[136:139], v[216:219], v[48:51]
	v_mfma_f32_16x16x32_bf16 v[44:47], v[144:147], v[216:219], v[44:47]
	v_mfma_f32_16x16x32_bf16 v[40:43], v[136:139], v[224:227], v[40:43]
	v_mfma_f32_16x16x32_bf16 v[36:39], v[144:147], v[224:227], v[36:39]
	v_mfma_f32_16x16x32_bf16 v[32:35], v[148:151], v[188:191], v[32:35]
	v_mfma_f32_16x16x32_bf16 v[28:31], v[156:159], v[188:191], v[28:31]
	v_mfma_f32_16x16x32_bf16 v[24:27], v[148:151], v[196:199], v[24:27]
	v_mfma_f32_16x16x32_bf16 v[20:23], v[156:159], v[196:199], v[20:23]
	v_mfma_f32_16x16x32_bf16 v[16:19], v[148:151], v[212:215], v[16:19]
	v_mfma_f32_16x16x32_bf16 v[12:15], v[156:159], v[212:215], v[12:15]
	v_mfma_f32_16x16x32_bf16 v[6:9], v[148:151], v[220:223], v[8:11]
	v_mfma_f32_16x16x32_bf16 v[2:5], v[156:159], v[220:223], v[2:5]
	v_mfma_f32_16x16x32_bf16 v[32:35], v[152:155], v[192:195], v[32:35]
	v_mfma_f32_16x16x32_bf16 v[28:31], v[184:187], v[192:195], v[28:31]
	v_mfma_f32_16x16x32_bf16 v[24:27], v[152:155], v[208:211], v[24:27]
	v_mfma_f32_16x16x32_bf16 v[20:23], v[184:187], v[208:211], v[20:23]
	v_mfma_f32_16x16x32_bf16 v[16:19], v[152:155], v[216:219], v[16:19]
	v_mfma_f32_16x16x32_bf16 v[12:15], v[184:187], v[216:219], v[12:15]
	v_mfma_f32_16x16x32_bf16 v[8:11], v[152:155], v[224:227], v[6:9]
	v_mfma_f32_16x16x32_bf16 v[4:7], v[184:187], v[224:227], v[2:5]
	s_barrier
	s_setprio 0
	s_add_u32 s29, s29, 0x10000
	s_addc_u32 s74, s74, 0
	s_add_u32 s16, s16, 0x10000
	s_addc_u32 s17, s17, 0
	s_cmp_ge_i32 s75, s39
	s_mov_b32 s72, s75
	s_cbranch_scc0 .LBB7_434
	s_branch .Lpeelx_434

.Lpeelx_434:
.LBB7_435:
	s_and_b64 vcc, exec, s[12:13]
	s_cbranch_vccz .LBB7_437
	s_barrier

.LBB7_1093:
	v_readlane_b32 s16, v250, 4
	v_mov_b32_e32 v177, v1
	v_readlane_b32 s17, v250, 5
	v_mov_b32_e32 v161, v1
	v_readlane_b32 s14, v253, 22
	v_lshl_add_u64 v[8:9], s[16:17], 0, v[176:177]
	v_lshl_add_u64 v[10:11], s[16:17], 0, v[160:161]
	v_mov_b32_e32 v179, v1
	v_readlane_b32 s15, v253, 23
	s_add_i32 m0, s5, 0x18000
	v_lshl_add_u64 v[8:9], v[8:9], 0, s[24:25]
	v_lshl_add_u64 v[12:13], s[14:15], 0, v[178:179]
	v_mov_b32_e32 v175, v1
	s_waitcnt vmcnt(2)
	s_barrier
	global_load_lds_dwordx4 v[8:9], off
	v_lshl_add_u64 v[8:9], v[10:11], 0, s[24:25]
	s_add_i32 m0, s5, 0x1a000
	s_add_i32 s33, s5, 0x8000
	v_lshl_add_u64 v[14:15], s[14:15], 0, v[174:175]
	global_load_lds_dwordx4 v[8:9], off
	v_lshl_add_u64 v[8:9], v[12:13], 0, s[24:25]
	s_mov_b32 m0, s33
	s_add_i32 s38, s5, 0xa000
	v_readlane_b32 s12, v250, 6
	global_load_lds_dwordx4 v[8:9], off
	v_lshl_add_u64 v[8:9], v[14:15], 0, s[24:25]
	s_mov_b32 m0, s38
	v_readlane_b32 s13, v250, 7
	global_load_lds_dwordx4 v[8:9], off
	s_add_i32 m0, s5, 0x1c000
	v_lshl_add_u64 v[8:9], s[12:13], 0, v[176:177]
	global_load_lds_dwordx4 v[8:9], off
	v_lshl_add_u64 v[8:9], s[12:13], 0, v[160:161]
	s_add_i32 m0, s5, 0x1e000
	s_and_b32 s92, s7, 3
	global_load_lds_dwordx4 v[8:9], off
	v_bfe_u32 v9, v0, 4, 2
	v_and_b32_e32 v8, 15, v0
	v_lshlrev_b32_e32 v11, 4, v9
	v_lshlrev_b32_e32 v0, 2, v0
	v_lshl_or_b32 v204, s8, 6, v8
	v_lshl_or_b32 v8, v8, 6, v11
	s_lshl_b32 s7, s8, 13
	v_and_b32_e32 v0, 32, v0
	v_bitop3_b32 v11, v8, s7, v0 bitop3:0xde
	s_lshl_b32 s7, s92, 12
	v_bitop3_b32 v205, v8, s7, v0 bitop3:0xde
	v_lshlrev_b32_e32 v0, 14, v6
	v_and_b32_e32 v0, 0xffff8000, v0
	v_lshl_add_u32 v0, v5, 11, v0
	v_and_b32_e32 v5, 1, v6
	v_lshl_or_b32 v0, v5, 6, v0
	v_lshl_add_u32 v180, v7, 1, v0
	v_lshlrev_b32_e32 v0, 14, v2
	v_and_b32_e32 v0, 0xffff8000, v0
	v_lshl_add_u32 v0, v3, 11, v0
	v_and_b32_e32 v2, 1, v2
	v_lshlrev_b32_e32 v10, 3, v9
	s_waitcnt vmcnt(6)
	s_cmpk_lt_u32 s6, 0x100
	v_lshl_or_b32 v0, v2, 6, v0
	v_mov_b32_e32 v2, v1
	v_mov_b32_e32 v3, v1
	v_lshl_or_b32 v206, s92, 5, v10
	s_cselect_b64 s[6:7], -1, 0
	v_cmp_eq_u32_e64 s[40:41], 0, v9
	s_cmp_gt_i32 s3, 0
	v_lshl_add_u32 v182, v4, 1, v0
	v_mov_b32_e32 v0, v1
	v_add_u32_e32 v207, 0, v11
	v_readlane_b32 s12, v253, 5
	s_mov_b32 s56, 0
	s_cselect_b64 s[8:9], -1, 0
	s_add_i32 s39, s3, -2
	v_mov_b32_e32 v181, v1
	v_mov_b32_e32 v183, v1
	v_readlane_b32 s57, v252, 22
	s_mov_b32 s88, s12
	s_barrier
	v_readlane_b32 s13, v253, 6
	s_branch .LBB7_1096
.LBB7_1094:
	s_waitcnt lgkmcnt(0)
	v_mov_b32_e32 v2, v1
	v_mov_b32_e32 v3, v1
	v_mov_b32_e32 v0, v1
	s_mov_b32 s57, s18
	s_mov_b32 s88, s48
	s_mov_b64 s[16:17], s[12:13]
	s_mov_b64 s[14:15], s[54:55]
	s_mov_b32 s56, s10

.Lpeel_1104:
	s_add_i32 s74, s72, 2
	s_add_u32 s75, vcc_lo, 0xfffc0080
	s_addc_u32 s73, vcc_hi, -1
	s_add_i32 s76, 0, 0x10000
	s_cmp_eq_u32 s39, s72
	s_cselect_b32 s73, s19, s73
	s_cselect_b32 s72, s20, s75
	v_add_u32_e32 v0, s76, v205
	s_cselect_b32 s85, s28, s49
	s_cselect_b32 s84, s29, s37
	s_add_i32 s75, 0, 0x14000
	ds_read_b128 v[132:135], v0
	ds_read_b128 v[136:139], v0 offset:1024
	ds_read_b128 v[140:143], v0 offset:2048
	ds_read_b128 v[144:147], v0 offset:3072
	v_add_u32_e32 v0, s75, v205
	ds_read_b128 v[148:151], v0
	ds_read_b128 v[152:155], v0 offset:1024
	ds_read_b128 v[156:159], v0 offset:2048
	ds_read_b128 v[184:187], v0 offset:3072
	s_waitcnt lgkmcnt(0)
	s_add_i32 m0, s5, 0xc000
	ds_read_b128 v[188:191], v207
	ds_read_b128 v[192:195], v207 offset:1024
	ds_read_b128 v[196:199], v207 offset:2048
	ds_read_b128 v[208:211], v207 offset:3072
	ds_read_b128 v[212:215], v207 offset:4096
	ds_read_b128 v[216:219], v207 offset:5120
	ds_read_b128 v[220:223], v207 offset:6144
	ds_read_b128 v[224:227], v207 offset:7168
	global_load_lds_dwordx4 v180, vcc
	s_add_i32 m0, s5, 0xe000
	s_nop 0
	global_load_lds_dwordx4 v182, vcc
	s_waitcnt vmcnt(8)
	s_waitcnt lgkmcnt(0)
	s_setprio 1
	s_barrier
	v_mfma_f32_16x16x32_bf16 v[128:131], v[132:135], v[188:191], 0
	v_mfma_f32_16x16x32_bf16 v[124:127], v[140:143], v[188:191], 0
	v_mfma_f32_16x16x32_bf16 v[120:123], v[132:135], v[196:199], 0
	v_mfma_f32_16x16x32_bf16 v[116:119], v[140:143], v[196:199], 0
	v_mfma_f32_16x16x32_bf16 v[112:115], v[132:135], v[212:215], 0
	v_mfma_f32_16x16x32_bf16 v[108:111], v[140:143], v[212:215], 0
	v_mfma_f32_16x16x32_bf16 v[104:107], v[132:135], v[220:223], 0
	v_mfma_f32_16x16x32_bf16 v[100:103], v[140:143], v[220:223], 0
	v_mfma_f32_16x16x32_bf16 v[128:131], v[136:139], v[192:195], v[128:131]
	v_mfma_f32_16x16x32_bf16 v[124:127], v[144:147], v[192:195], v[124:127]
	v_mfma_f32_16x16x32_bf16 v[120:123], v[136:139], v[208:211], v[120:123]
	v_mfma_f32_16x16x32_bf16 v[116:119], v[144:147], v[208:211], v[116:119]
	v_mfma_f32_16x16x32_bf16 v[112:115], v[136:139], v[216:219], v[112:115]
	v_mfma_f32_16x16x32_bf16 v[108:111], v[144:147], v[216:219], v[108:111]
	v_mfma_f32_16x16x32_bf16 v[104:107], v[136:139], v[224:227], v[104:107]
	v_mfma_f32_16x16x32_bf16 v[100:103], v[144:147], v[224:227], v[100:103]
	v_mfma_f32_16x16x32_bf16 v[96:99], v[148:151], v[188:191], 0
	v_mfma_f32_16x16x32_bf16 v[92:95], v[156:159], v[188:191], 0
	v_mfma_f32_16x16x32_bf16 v[88:91], v[148:151], v[196:199], 0
	v_mfma_f32_16x16x32_bf16 v[84:87], v[156:159], v[196:199], 0
	v_mfma_f32_16x16x32_bf16 v[80:83], v[148:151], v[212:215], 0
	v_mfma_f32_16x16x32_bf16 v[76:79], v[156:159], v[212:215], 0
	v_mfma_f32_16x16x32_bf16 v[72:75], v[148:151], v[220:223], 0
	v_mfma_f32_16x16x32_bf16 v[68:71], v[156:159], v[220:223], 0
	v_mfma_f32_16x16x32_bf16 v[96:99], v[152:155], v[192:195], v[96:99]
	v_mfma_f32_16x16x32_bf16 v[92:95], v[184:187], v[192:195], v[92:95]
	v_mfma_f32_16x16x32_bf16 v[88:91], v[152:155], v[208:211], v[88:91]
	v_mfma_f32_16x16x32_bf16 v[84:87], v[184:187], v[208:211], v[84:87]
	v_mfma_f32_16x16x32_bf16 v[80:83], v[152:155], v[216:219], v[80:83]
	v_mfma_f32_16x16x32_bf16 v[76:79], v[184:187], v[216:219], v[76:79]
	v_mfma_f32_16x16x32_bf16 v[72:75], v[152:155], v[224:227], v[72:75]
	v_mfma_f32_16x16x32_bf16 v[68:71], v[184:187], v[224:227], v[68:71]
	s_barrier
	s_setprio 0
	s_add_i32 s76, s76, s4
	v_lshl_add_u64 v[170:171], s[84:85], 0, v[176:177]
	s_mov_b32 m0, s76
	ds_read_b128 v[188:191], v207 offset:16384
	ds_read_b128 v[192:195], v207 offset:17408
	ds_read_b128 v[196:199], v207 offset:18432
	ds_read_b128 v[208:211], v207 offset:19456
	ds_read_b128 v[212:215], v207 offset:20480
	ds_read_b128 v[216:219], v207 offset:21504
	ds_read_b128 v[220:223], v207 offset:22528
	ds_read_b128 v[224:227], v207 offset:23552
	global_load_lds_dwordx4 v[170:171], off
	s_add_i32 m0, s76, 0x2000
	s_add_u32 s76, s84, 0x40000
	v_lshl_add_u64 v[172:173], s[84:85], 0, v[160:161]
	s_addc_u32 s77, s85, 0
	s_add_i32 s75, s75, s4
	global_load_lds_dwordx4 v[172:173], off
	s_mov_b32 m0, s75
	v_lshl_add_u64 v[228:229], s[72:73], 0, v[178:179]
	global_load_lds_dwordx4 v176, s[76:77]
	s_add_i32 m0, s75, 0x2000
	v_lshl_add_u64 v[230:231], s[72:73], 0, v[174:175]
	global_load_lds_dwordx4 v160, s[76:77]
	s_mov_b32 m0, s5
	s_nop 0
	global_load_lds_dwordx4 v[228:229], off
	s_mov_b32 m0, s22
	s_nop 0
	global_load_lds_dwordx4 v[230:231], off
	s_waitcnt vmcnt(8)
	s_waitcnt lgkmcnt(0)
	s_setprio 1
	s_barrier
	v_mfma_f32_16x16x32_bf16 v[64:67], v[132:135], v[188:191], 0
	v_mfma_f32_16x16x32_bf16 v[60:63], v[140:143], v[188:191], 0
	v_mfma_f32_16x16x32_bf16 v[56:59], v[132:135], v[196:199], 0
	v_mfma_f32_16x16x32_bf16 v[52:55], v[140:143], v[196:199], 0
	v_mfma_f32_16x16x32_bf16 v[48:51], v[132:135], v[212:215], 0
	v_mfma_f32_16x16x32_bf16 v[44:47], v[140:143], v[212:215], 0
	v_mfma_f32_16x16x32_bf16 v[40:43], v[132:135], v[220:223], 0
	v_mfma_f32_16x16x32_bf16 v[36:39], v[140:143], v[220:223], 0
	v_mfma_f32_16x16x32_bf16 v[64:67], v[136:139], v[192:195], v[64:67]
	v_mfma_f32_16x16x32_bf16 v[60:63], v[144:147], v[192:195], v[60:63]
	v_mfma_f32_16x16x32_bf16 v[56:59], v[136:139], v[208:211], v[56:59]
	v_mfma_f32_16x16x32_bf16 v[52:55], v[144:147], v[208:211], v[52:55]
	v_mfma_f32_16x16x32_bf16 v[48:51], v[136:139], v[216:219], v[48:51]
	v_mfma_f32_16x16x32_bf16 v[44:47], v[144:147], v[216:219], v[44:47]
	v_mfma_f32_16x16x32_bf16 v[40:43], v[136:139], v[224:227], v[40:43]
	v_mfma_f32_16x16x32_bf16 v[36:39], v[144:147], v[224:227], v[36:39]
	v_mfma_f32_16x16x32_bf16 v[32:35], v[148:151], v[188:191], 0
	v_mfma_f32_16x16x32_bf16 v[28:31], v[156:159], v[188:191], 0
	v_mfma_f32_16x16x32_bf16 v[24:27], v[148:151], v[196:199], 0
	v_mfma_f32_16x16x32_bf16 v[20:23], v[156:159], v[196:199], 0
	v_mfma_f32_16x16x32_bf16 v[16:19], v[148:151], v[212:215], 0
	v_mfma_f32_16x16x32_bf16 v[12:15], v[156:159], v[212:215], 0
	v_mfma_f32_16x16x32_bf16 v[8:11], v[148:151], v[220:223], 0
	v_mfma_f32_16x16x32_bf16 v[2:5], v[156:159], v[220:223], 0
	v_mfma_f32_16x16x32_bf16 v[32:35], v[152:155], v[192:195], v[32:35]
	v_mfma_f32_16x16x32_bf16 v[28:31], v[184:187], v[192:195], v[28:31]
	v_mfma_f32_16x16x32_bf16 v[24:27], v[152:155], v[208:211], v[24:27]
	v_mfma_f32_16x16x32_bf16 v[20:23], v[184:187], v[208:211], v[20:23]
	v_mfma_f32_16x16x32_bf16 v[16:19], v[152:155], v[216:219], v[16:19]
	v_mfma_f32_16x16x32_bf16 v[12:15], v[184:187], v[216:219], v[12:15]
	v_mfma_f32_16x16x32_bf16 v[8:11], v[152:155], v[224:227], v[8:11]
	v_mfma_f32_16x16x32_bf16 v[2:5], v[184:187], v[224:227], v[2:5]
	s_barrier
	s_setprio 0
	s_add_i32 s75, 0, 0x18000
	v_add_u32_e32 v0, s75, v205
	s_add_i32 s76, 0, 0x1c000
	ds_read_b128 v[132:135], v0
	ds_read_b128 v[136:139], v0 offset:1024
	ds_read_b128 v[140:143], v0 offset:2048
	ds_read_b128 v[144:147], v0 offset:3072
	v_add_u32_e32 v0, s76, v205
	ds_read_b128 v[148:151], v0
	ds_read_b128 v[152:155], v0 offset:1024
	ds_read_b128 v[156:159], v0 offset:2048
	ds_read_b128 v[184:187], v0 offset:3072
	s_add_u32 s72, s72, 0x40000
	s_addc_u32 s73, s73, 0
	s_mov_b32 m0, s23
	ds_read_b128 v[188:191], v207 offset:32768
	ds_read_b128 v[192:195], v207 offset:33792
	ds_read_b128 v[196:199], v207 offset:34816
	ds_read_b128 v[208:211], v207 offset:35840
	ds_read_b128 v[212:215], v207 offset:36864
	ds_read_b128 v[216:219], v207 offset:37888
	ds_read_b128 v[220:223], v207 offset:38912
	ds_read_b128 v[224:227], v207 offset:39936
	global_load_lds_dwordx4 v178, s[72:73]
	s_mov_b32 m0, s31
	s_nop 0
	global_load_lds_dwordx4 v174, s[72:73]
	s_waitcnt vmcnt(8)
	s_waitcnt lgkmcnt(0)
	s_setprio 1
	s_barrier
	v_mfma_f32_16x16x32_bf16 v[128:131], v[132:135], v[188:191], v[128:131]
	v_mfma_f32_16x16x32_bf16 v[124:127], v[140:143], v[188:191], v[124:127]
	v_mfma_f32_16x16x32_bf16 v[120:123], v[132:135], v[196:199], v[120:123]
	v_mfma_f32_16x16x32_bf16 v[116:119], v[140:143], v[196:199], v[116:119]
	v_mfma_f32_16x16x32_bf16 v[112:115], v[132:135], v[212:215], v[112:115]
	v_mfma_f32_16x16x32_bf16 v[108:111], v[140:143], v[212:215], v[108:111]
	v_mfma_f32_16x16x32_bf16 v[104:107], v[132:135], v[220:223], v[104:107]
	v_mfma_f32_16x16x32_bf16 v[100:103], v[140:143], v[220:223], v[100:103]
	v_mfma_f32_16x16x32_bf16 v[128:131], v[136:139], v[192:195], v[128:131]
	v_mfma_f32_16x16x32_bf16 v[124:127], v[144:147], v[192:195], v[124:127]
	v_mfma_f32_16x16x32_bf16 v[120:123], v[136:139], v[208:211], v[120:123]
	v_mfma_f32_16x16x32_bf16 v[116:119], v[144:147], v[208:211], v[116:119]
	v_mfma_f32_16x16x32_bf16 v[112:115], v[136:139], v[216:219], v[112:115]
	v_mfma_f32_16x16x32_bf16 v[108:111], v[144:147], v[216:219], v[108:111]
	v_mfma_f32_16x16x32_bf16 v[104:107], v[136:139], v[224:227], v[104:107]
	v_mfma_f32_16x16x32_bf16 v[100:103], v[144:147], v[224:227], v[100:103]
	v_mfma_f32_16x16x32_bf16 v[96:99], v[148:151], v[188:191], v[96:99]
	v_mfma_f32_16x16x32_bf16 v[92:95], v[156:159], v[188:191], v[92:95]
	v_mfma_f32_16x16x32_bf16 v[88:91], v[148:151], v[196:199], v[88:91]
	v_mfma_f32_16x16x32_bf16 v[84:87], v[156:159], v[196:199], v[84:87]
	v_mfma_f32_16x16x32_bf16 v[80:83], v[148:151], v[212:215], v[80:83]
	v_mfma_f32_16x16x32_bf16 v[76:79], v[156:159], v[212:215], v[76:79]
	v_mfma_f32_16x16x32_bf16 v[72:75], v[148:151], v[220:223], v[72:75]
	v_mfma_f32_16x16x32_bf16 v[68:71], v[156:159], v[220:223], v[68:71]
	v_mfma_f32_16x16x32_bf16 v[96:99], v[152:155], v[192:195], v[96:99]
	v_mfma_f32_16x16x32_bf16 v[92:95], v[184:187], v[192:195], v[92:95]
	v_mfma_f32_16x16x32_bf16 v[88:91], v[152:155], v[208:211], v[88:91]
	v_mfma_f32_16x16x32_bf16 v[84:87], v[184:187], v[208:211], v[84:87]
	v_mfma_f32_16x16x32_bf16 v[80:83], v[152:155], v[216:219], v[80:83]
	v_mfma_f32_16x16x32_bf16 v[76:79], v[184:187], v[216:219], v[76:79]
	v_mfma_f32_16x16x32_bf16 v[72:75], v[152:155], v[224:227], v[72:75]
	v_mfma_f32_16x16x32_bf16 v[68:71], v[184:187], v[224:227], v[68:71]
	s_barrier
	s_setprio 0
	s_add_i32 s72, s75, s4
	v_lshl_add_u64 v[6:7], v[170:171], 0, s[24:25]
	s_mov_b32 m0, s72
	ds_read_b128 v[188:191], v207 offset:49152
	ds_read_b128 v[192:195], v207 offset:50176
	ds_read_b128 v[196:199], v207 offset:51200
	ds_read_b128 v[208:211], v207 offset:52224
	ds_read_b128 v[212:215], v207 offset:53248
	ds_read_b128 v[216:219], v207 offset:54272
	ds_read_b128 v[220:223], v207 offset:55296
	ds_read_b128 v[224:227], v207 offset:56320
	global_load_lds_dwordx4 v[6:7], off
	s_add_i32 m0, s72, 0x2000
	s_add_u32 s72, s84, 0x40080
	v_lshl_add_u64 v[6:7], v[172:173], 0, s[24:25]
	s_addc_u32 s73, s85, 0
	s_add_i32 s75, s76, s4
	global_load_lds_dwordx4 v[6:7], off
	s_mov_b32 m0, s75
	s_nop 0
	global_load_lds_dwordx4 v176, s[72:73]
	s_add_i32 m0, s75, 0x2000
	s_nop 0
	global_load_lds_dwordx4 v160, s[72:73]
	v_lshl_add_u64 v[6:7], v[228:229], 0, s[24:25]
	s_mov_b32 m0, s33
	s_nop 0
	global_load_lds_dwordx4 v[6:7], off
	v_lshl_add_u64 v[6:7], v[230:231], 0, s[24:25]
	s_mov_b32 m0, s38
	s_nop 0
	global_load_lds_dwordx4 v[6:7], off
	s_waitcnt vmcnt(8)
	s_waitcnt lgkmcnt(0)
	s_setprio 1
	s_barrier
	v_mfma_f32_16x16x32_bf16 v[64:67], v[132:135], v[188:191], v[64:67]
	v_mfma_f32_16x16x32_bf16 v[60:63], v[140:143], v[188:191], v[60:63]
	v_mfma_f32_16x16x32_bf16 v[56:59], v[132:135], v[196:199], v[56:59]
	v_mfma_f32_16x16x32_bf16 v[52:55], v[140:143], v[196:199], v[52:55]
	v_mfma_f32_16x16x32_bf16 v[48:51], v[132:135], v[212:215], v[48:51]
	v_mfma_f32_16x16x32_bf16 v[44:47], v[140:143], v[212:215], v[44:47]
	v_mfma_f32_16x16x32_bf16 v[40:43], v[132:135], v[220:223], v[40:43]
	v_mfma_f32_16x16x32_bf16 v[36:39], v[140:143], v[220:223], v[36:39]
	v_mfma_f32_16x16x32_bf16 v[64:67], v[136:139], v[192:195], v[64:67]
	v_mfma_f32_16x16x32_bf16 v[60:63], v[144:147], v[192:195], v[60:63]
	v_mfma_f32_16x16x32_bf16 v[56:59], v[136:139], v[208:211], v[56:59]
	v_mfma_f32_16x16x32_bf16 v[52:55], v[144:147], v[208:211], v[52:55]
	v_mfma_f32_16x16x32_bf16 v[48:51], v[136:139], v[216:219], v[48:51]
	v_mfma_f32_16x16x32_bf16 v[44:47], v[144:147], v[216:219], v[44:47]
	v_mfma_f32_16x16x32_bf16 v[40:43], v[136:139], v[224:227], v[40:43]
	v_mfma_f32_16x16x32_bf16 v[36:39], v[144:147], v[224:227], v[36:39]
	v_mfma_f32_16x16x32_bf16 v[32:35], v[148:151], v[188:191], v[32:35]
	v_mfma_f32_16x16x32_bf16 v[28:31], v[156:159], v[188:191], v[28:31]
	v_mfma_f32_16x16x32_bf16 v[24:27], v[148:151], v[196:199], v[24:27]
	v_mfma_f32_16x16x32_bf16 v[20:23], v[156:159], v[196:199], v[20:23]
	v_mfma_f32_16x16x32_bf16 v[16:19], v[148:151], v[212:215], v[16:19]
	v_mfma_f32_16x16x32_bf16 v[12:15], v[156:159], v[212:215], v[12:15]
	v_mfma_f32_16x16x32_bf16 v[6:9], v[148:151], v[220:223], v[8:11]
	v_mfma_f32_16x16x32_bf16 v[2:5], v[156:159], v[220:223], v[2:5]
	v_mfma_f32_16x16x32_bf16 v[32:35], v[152:155], v[192:195], v[32:35]
	v_mfma_f32_16x16x32_bf16 v[28:31], v[184:187], v[192:195], v[28:31]
	v_mfma_f32_16x16x32_bf16 v[24:27], v[152:155], v[208:211], v[24:27]
	v_mfma_f32_16x16x32_bf16 v[20:23], v[184:187], v[208:211], v[20:23]
	v_mfma_f32_16x16x32_bf16 v[16:19], v[152:155], v[216:219], v[16:19]
	v_mfma_f32_16x16x32_bf16 v[12:15], v[184:187], v[216:219], v[12:15]
	v_mfma_f32_16x16x32_bf16 v[8:11], v[152:155], v[224:227], v[6:9]
	v_mfma_f32_16x16x32_bf16 v[4:7], v[184:187], v[224:227], v[2:5]
	s_barrier
	s_setprio 0
	s_add_u32 s37, s37, 0x100
	s_addc_u32 s49, s49, 0
	s_add_u32 vcc_lo, vcc_lo, 0x100
	s_addc_u32 vcc_hi, vcc_hi, 0
	s_cmp_ge_i32 s74, s3
	s_mov_b32 s72, s74
	s_cbranch_scc0 .LBB7_1104
	s_branch .Lpeelx_1104

.Lpeelx_1104:
.LBB7_1105:
	s_and_b64 vcc, exec, s[6:7]
	s_cbranch_vccz .LBB7_1107
	s_barrier

.LBB7_1340:
	v_readlane_b32 s16, v250, 22
	v_mov_b32_e32 v177, v1
	v_readlane_b32 s17, v250, 23
	v_mov_b32_e32 v161, v1
	v_readlane_b32 s14, v253, 33
	v_lshl_add_u64 v[8:9], s[16:17], 0, v[176:177]
	v_lshl_add_u64 v[10:11], s[16:17], 0, v[160:161]
	v_mov_b32_e32 v179, v1
	v_readlane_b32 s15, v253, 34
	s_add_i32 m0, s5, 0x18000
	v_lshl_add_u64 v[8:9], v[8:9], 0, s[24:25]
	v_lshl_add_u64 v[12:13], s[14:15], 0, v[178:179]
	v_mov_b32_e32 v175, v1
	s_waitcnt vmcnt(2)
	s_barrier
	global_load_lds_dwordx4 v[8:9], off
	v_lshl_add_u64 v[8:9], v[10:11], 0, s[24:25]
	s_add_i32 m0, s5, 0x1a000
	s_add_i32 s33, s5, 0x8000
	v_lshl_add_u64 v[14:15], s[14:15], 0, v[174:175]
	global_load_lds_dwordx4 v[8:9], off
	v_lshl_add_u64 v[8:9], v[12:13], 0, s[24:25]
	s_mov_b32 m0, s33
	s_add_i32 s38, s5, 0xa000
	v_readlane_b32 s12, v250, 24
	global_load_lds_dwordx4 v[8:9], off
	v_lshl_add_u64 v[8:9], v[14:15], 0, s[24:25]
	s_mov_b32 m0, s38
	v_readlane_b32 s13, v250, 25
	global_load_lds_dwordx4 v[8:9], off
	s_add_i32 m0, s5, 0x1c000
	v_lshl_add_u64 v[8:9], s[12:13], 0, v[176:177]
	global_load_lds_dwordx4 v[8:9], off
	v_lshl_add_u64 v[8:9], s[12:13], 0, v[160:161]
	s_add_i32 m0, s5, 0x1e000
	s_and_b32 s92, s7, 3
	global_load_lds_dwordx4 v[8:9], off
	v_bfe_u32 v9, v0, 4, 2
	v_and_b32_e32 v8, 15, v0
	v_lshlrev_b32_e32 v11, 4, v9
	v_lshlrev_b32_e32 v0, 2, v0
	v_lshl_or_b32 v204, s8, 6, v8
	v_lshl_or_b32 v8, v8, 6, v11
	s_lshl_b32 s7, s8, 13
	v_and_b32_e32 v0, 32, v0
	v_bitop3_b32 v11, v8, s7, v0 bitop3:0xde
	s_lshl_b32 s7, s92, 12
	v_bitop3_b32 v205, v8, s7, v0 bitop3:0xde
	v_lshlrev_b32_e32 v0, 14, v6
	v_and_b32_e32 v0, 0xffff8000, v0
	v_lshl_add_u32 v0, v5, 11, v0
	v_and_b32_e32 v5, 1, v6
	v_lshl_or_b32 v0, v5, 6, v0
	v_lshl_add_u32 v180, v7, 1, v0
	v_lshlrev_b32_e32 v0, 14, v2
	v_and_b32_e32 v0, 0xffff8000, v0
	v_lshl_add_u32 v0, v3, 11, v0
	v_and_b32_e32 v2, 1, v2
	v_lshlrev_b32_e32 v10, 3, v9
	s_waitcnt vmcnt(6)
	s_cmpk_lt_u32 s6, 0x100
	v_lshl_or_b32 v0, v2, 6, v0
	v_mov_b32_e32 v2, v1
	v_mov_b32_e32 v3, v1
	v_readlane_b32 s12, v253, 5
	v_lshl_or_b32 v206, s92, 5, v10
	s_cselect_b64 s[6:7], -1, 0
	v_cmp_eq_u32_e64 s[40:41], 0, v9
	s_cmp_gt_i32 s3, 0
	v_lshl_add_u32 v182, v4, 1, v0
	v_mov_b32_e32 v0, v1
	v_add_u32_e32 v207, 0, v11
	v_readlane_b32 s13, v253, 6
	s_mov_b32 s56, 0
	s_cselect_b64 s[8:9], -1, 0
	s_add_i32 s39, s3, -2
	v_mov_b32_e32 v181, v1
	v_mov_b32_e32 v183, v1
	v_readlane_b32 s57, v252, 22
	s_mov_b32 s88, s12
	s_mov_b64 s[12:13], s[16:17]
	s_barrier
	s_branch .LBB7_1343
.LBB7_1341:
	s_waitcnt lgkmcnt(0)
	v_mov_b32_e32 v2, v1
	v_mov_b32_e32 v3, v1
	v_mov_b32_e32 v0, v1
	s_mov_b32 s57, s18
	s_mov_b32 s88, s48
	s_mov_b64 s[12:13], s[16:17]
	s_mov_b64 s[14:15], s[54:55]
	s_mov_b32 s56, s10
